# layer-1 expert-weight transposes tiles moved out of P0b into idle blocks of three layer-0 phases: in-proj third round (216 blocks x 16), top-k (448 x 4), layer-1 pre-norm (248 x 6)
# speedup vs baseline: 1.0090x; 1.0019x over previous
; __device__ __forceinline__ TrJob tr_decode(const Params& p, char* ws, int job) {
;   TrJob t;
;   int l = job / TJ_PER_LAYER, rj = job % TJ_PER_LAYER;
;   if (rj < 640) {
;     t.src = p.w_in + (size_t)l * 1024 * 2560; t.K = 1024; t.N = 2560; t.kt = rj / 40; t.nt = rj % 40;
;     t.dst = (u16*)(ws + OFF_WINT) + (size_t)l * 2560 * 1024; t.mode = 0;
;   } else if (rj < 896) {
;     rj -= 640;
;     t.src = p.w_out + (size_t)l * 1024 * 1024; t.K = 1024; t.N = 1024; t.kt = rj / 16; t.nt = rj % 16;
;     t.dst = (u16*)(ws + OFF_WOUTT) + (size_t)l * 1024 * 1024; t.mode = 0;
;   } else {
;     rj -= 896;
;     int e = rj / 1536, q = rj % 1536;
;     size_t eo = (size_t)(l * 16 + e);
;     if (q < 512) {
;       t.src = p.w_gate + eo * 1024 * 2048; t.K = 1024; t.N = 2048; t.kt = q / 32; t.nt = q % 32;
;       t.dst = (u16*)(ws + OFF_WGUT) + eo * 4096 * 1024; t.mode = 1;
;     } else if (q < 1024) {
;       q -= 512;
;       t.src = p.w_up + eo * 1024 * 2048; t.K = 1024; t.N = 2048; t.kt = q / 32; t.nt = q % 32;
;       t.dst = (u16*)(ws + OFF_WGUT) + eo * 4096 * 1024; t.mode = 2;
;     } else {
;       q -= 1024;
;       t.src = p.w_down + eo * 2048 * 1024; t.K = 2048; t.N = 1024; t.kt = q / 16; t.nt = q % 16;
;       t.dst = (u16*)(ws + OFF_WDT) + eo * 1024 * 2048; t.mode = 0;
;     }
; __device__ __forceinline__ void p0_transposes(const Params& p, char* smem, int bid, int nb, int jlo, int jhi) {
;     ...
;   int j = jlo + bid * 2;
;   if (j < jhi) { tr_load(p, ws, j, tid, c0); tr_load(p, ws, j + 1, tid, c1); }
;   for (; j < jhi; j += 2 * nb) {
;     const int jn = j + 2 * nb;
;     if (jn < jhi) { tr_load(p, ws, jn, tid, n0); tr_load(p, ws, jn + 1, tid, n1); }
.LBB0_174:
	s_add_i32 s96, s97, s75
	s_cmp_gt_i32 s96, 0x84af
	s_cselect_b64 s[0:1], -1, 0
	s_and_b64 vcc, exec, s[0:1]
	s_cbranch_vccnz .LBB0_208
	s_mul_hi_i32 s10, s96, 0x5254e78f
	s_lshr_b32 s11, s10, 31
	s_ashr_i32 s10, s10, 13
	s_add_i32 s52, s10, s11
	s_mul_i32 s10, s52, 0xffff9c80
	s_add_i32 s10, s96, s10
	s_cmpk_gt_i32 s10, 0x27f
	s_mov_b64 s[58:59], -1
	s_cbranch_scc0 .LBB0_189
	s_cmpk_gt_u32 s10, 0x37f
	s_cbranch_scc0 .LBB0_186
	s_add_i32 s11, s10, 0xfc80
	s_and_b32 s33, s11, 0xffff
	s_mul_i32 s33, s33, 0xaaab
	s_lshr_b32 s33, s33, 26
	s_mul_i32 s40, s33, 0x600
	s_sub_i32 s11, s11, s40
	s_and_b32 s40, s11, 0xffff
	s_lshl_b32 s11, s52, 4
	s_add_i32 s54, s11, s33
	s_ashr_i32 s55, s54, 31
	s_lshl_b64 s[58:59], s[54:55], 23
	s_cmpk_gt_u32 s40, 0x1ff
	s_mov_b64 s[60:61], -1
	s_cbranch_scc0 .LBB0_183
	s_cmpk_gt_u32 s40, 0x3ff
	s_mov_b64 s[56:57], -1
	s_cbranch_scc0 .LBB0_180
	v_readlane_b32 s12, v238, 25
	s_add_i32 s11, s40, 0xfffffc00
	v_readlane_b32 s18, v238, 31
	v_readlane_b32 s19, v238, 32
	s_add_u32 s54, s18, s58
	v_readlane_b32 s13, v238, 26
	v_readlane_b32 s14, v238, 27
	v_readlane_b32 s15, v238, 28
	v_readlane_b32 s16, v238, 29
	v_readlane_b32 s17, v238, 30
	s_addc_u32 s55, s19, s59
	s_lshr_b32 s33, s11, 4
	s_and_b32 s11, s40, 15
	s_mov_b64 s[56:57], 0

; #define GSYNC() do { xcd_barrier(xb); if (REP_MASK & 256) xcd_barrier(xb); } while (0)
; __device__ __forceinline__ TrJob tr_decode(const Params& p, char* ws, int job) {
;   TrJob t;
;   int l = job / TJ_PER_LAYER, rj = job % TJ_PER_LAYER;
;   if (rj < 640) {
;     t.src = p.w_in + (size_t)l * 1024 * 2560; t.K = 1024; t.N = 2560; t.kt = rj / 40; t.nt = rj % 40;
;     t.dst = (u16*)(ws + OFF_WINT) + (size_t)l * 2560 * 1024; t.mode = 0;
;   } else if (rj < 896) {
;     rj -= 640;
;     t.src = p.w_out + (size_t)l * 1024 * 1024; t.K = 1024; t.N = 1024; t.kt = rj / 16; t.nt = rj % 16;
;     t.dst = (u16*)(ws + OFF_WOUTT) + (size_t)l * 1024 * 1024; t.mode = 0;
;   } else {
;     rj -= 896;
;     int e = rj / 1536, q = rj % 1536;
;     size_t eo = (size_t)(l * 16 + e);
;     if (q < 512) {
;       t.src = p.w_gate + eo * 1024 * 2048; t.K = 1024; t.N = 2048; t.kt = q / 32; t.nt = q % 32;
;       t.dst = (u16*)(ws + OFF_WGUT) + eo * 4096 * 1024; t.mode = 1;
;     } else if (q < 1024) {
;       q -= 512;
;       t.src = p.w_up + eo * 1024 * 2048; t.K = 1024; t.N = 2048; t.kt = q / 32; t.nt = q % 32;
;       t.dst = (u16*)(ws + OFF_WGUT) + eo * 4096 * 1024; t.mode = 2;
;     } else {
;       q -= 1024;
;       t.src = p.w_down + eo * 2048 * 1024; t.K = 2048; t.N = 1024; t.kt = q / 16; t.nt = q % 16;
;       t.dst = (u16*)(ws + OFF_WDT) + eo * 1024 * 2048; t.mode = 0;
;     }
; __global__ void __launch_bounds__(256, 2) fwd_megakernel(Params p) {
;     ...
;     for (int rep = 0; rep < NREP(5); ++rep) {
;       const int nj = l == 0 ? 64 : 32;
;       for (int j = bid; j < nj; j += nb) topk_job(p, smem, j & 31, j >= 32);
;       GSYNC();
.LBB0_1323:
	s_or_b64 exec, exec, s[0:1]
	v_readlane_b32 s0, v237, 29
	v_readlane_b32 s1, v237, 30
	s_and_b64 s[0:1], s[0:1], exec
	s_cselect_b32 s0, 64, 32
	v_readlane_b32 s2, v239, 0
	s_cmp_ge_i32 s2, s0
	s_waitcnt lgkmcnt(0)
	s_barrier
	v_writelane_b32 v237, s0, 32
	s_cbranch_scc0 .LBB0_1329
	v_readlane_b32 s0, v237, 29
	v_readlane_b32 s1, v237, 30
	s_and_b64 s[0:1], s[0:1], exec
	s_cbranch_scc0 .LBB0_1324
	v_readlane_b32 s100, v236, 62
	v_readlane_b32 s101, v236, 63
	v_writelane_b32 v255, s64, 0
	v_writelane_b32 v255, s65, 1
	v_writelane_b32 v255, s66, 2
	v_writelane_b32 v255, s67, 3
	v_writelane_b32 v255, s68, 4
	v_writelane_b32 v255, s69, 5
	v_writelane_b32 v255, s70, 6
	v_writelane_b32 v255, s71, 7
	v_writelane_b32 v255, s72, 8
	v_writelane_b32 v255, s73, 9
	v_writelane_b32 v255, s74, 10
	v_writelane_b32 v255, s75, 11
	v_writelane_b32 v255, s76, 12
	v_writelane_b32 v255, s77, 13
	v_writelane_b32 v255, s78, 14
	v_writelane_b32 v255, s79, 15
	v_writelane_b32 v255, s80, 16
	v_writelane_b32 v255, s81, 17
	v_writelane_b32 v255, s82, 18
	v_writelane_b32 v255, s83, 19
	v_writelane_b32 v255, s84, 20
	v_writelane_b32 v255, s85, 21
	v_writelane_b32 v255, s86, 22
	v_writelane_b32 v255, s87, 23
	v_writelane_b32 v255, s88, 24
	v_writelane_b32 v255, s89, 25
	v_writelane_b32 v255, s90, 26
	v_writelane_b32 v255, s91, 27
	v_writelane_b32 v255, s92, 28
	v_writelane_b32 v255, s93, 29
	v_writelane_b32 v255, s94, 30
	v_writelane_b32 v255, s95, 31
	v_writelane_b32 v255, s96, 32
	v_writelane_b32 v255, s97, 33
	v_writelane_b32 v255, s98, 34
	v_writelane_b32 v255, s99, 35
	v_writelane_b32 v255, vcc_lo, 36
	v_writelane_b32 v255, vcc_hi, 37
	s_load_dwordx4 s[64:67], s[100:101], 0x40
	s_load_dwordx4 s[68:71], s[100:101], 0xc8
	s_load_dwordx2 s[72:73], s[100:101], 0xd8
	s_load_dwordx2 s[74:75], s[100:101], 0xe8
	v_and_b32_e32 v241, 15, v172
	v_lshrrev_b32_e32 v242, 4, v172
	v_lshlrev_b32_e32 v241, 4, v241
	v_mul_u32_u24_e32 v243, 0x104, v242
	v_add_u32_e32 v243, v243, v241
	v_and_b32_e32 v246, 7, v172
	v_lshrrev_b32_e32 v245, 3, v172
	v_mul_u32_u24_e32 v244, 0x820, v246
	v_lshl_add_u32 v244, v245, 2, v244
	v_lshlrev_b32_e32 v246, 4, v246
	v_readlane_b32 s76, v239, 0
	s_add_u32 s76, s76, 35392
	s_movk_i32 s77, 2
	s_mov_b32 s96, 0
	s_waitcnt lgkmcnt(0)
.Ltrp5_batch:
	s_min_u32 s78, s76, 37247
	s_cmp_ge_u32 s78, 25472
	s_cselect_b32 s79, 1, 0
	s_cselect_b32 s85, 25472, 0
	s_sub_u32 s78, s78, s85
	s_cmp_lt_u32 s78, 640
	s_cbranch_scc0 .Ltr_p5l0_notin
	s_mul_hi_u32 s80, s78, 107374183
	s_mul_i32 s85, s80, 40
	s_sub_u32 s81, s78, s85
	s_movk_i32 s82, 2560
	s_movk_i32 s83, 1024
	s_mov_b32 s84, -1
	s_mul_i32 s85, s79, 10485760
	s_add_u32 s86, s64, s85
	s_addc_u32 s87, s65, 0
	s_mul_i32 s85, s79, 5242880
	s_add_u32 s88, s74, s85
	s_addc_u32 s89, s75, 0
	s_branch .Ltr_p5l0_dec_done

; __device__ __forceinline__ TrJob tr_decode(const Params& p, char* ws, int job) {
;   TrJob t;
;   int l = job / TJ_PER_LAYER, rj = job % TJ_PER_LAYER;
;   if (rj < 640) {
;     t.src = p.w_in + (size_t)l * 1024 * 2560; t.K = 1024; t.N = 2560; t.kt = rj / 40; t.nt = rj % 40;
;     t.dst = (u16*)(ws + OFF_WINT) + (size_t)l * 2560 * 1024; t.mode = 0;
;   } else if (rj < 896) {
;     rj -= 640;
;     t.src = p.w_out + (size_t)l * 1024 * 1024; t.K = 1024; t.N = 1024; t.kt = rj / 16; t.nt = rj % 16;
;     t.dst = (u16*)(ws + OFF_WOUTT) + (size_t)l * 1024 * 1024; t.mode = 0;
;   } else {
;     rj -= 896;
;     int e = rj / 1536, q = rj % 1536;
;     size_t eo = (size_t)(l * 16 + e);
;     if (q < 512) {
;       t.src = p.w_gate + eo * 1024 * 2048; t.K = 1024; t.N = 2048; t.kt = q / 32; t.nt = q % 32;
;       t.dst = (u16*)(ws + OFF_WGUT) + eo * 4096 * 1024; t.mode = 1;
;     } else if (q < 1024) {
;       q -= 512;
;       t.src = p.w_up + eo * 1024 * 2048; t.K = 1024; t.N = 2048; t.kt = q / 32; t.nt = q % 32;
;       t.dst = (u16*)(ws + OFF_WGUT) + eo * 4096 * 1024; t.mode = 2;
;     } else {
;       q -= 1024;
;       t.src = p.w_down + eo * 2048 * 1024; t.K = 2048; t.N = 1024; t.kt = q / 16; t.nt = q % 16;
;       t.dst = (u16*)(ws + OFF_WDT) + eo * 1024 * 2048; t.mode = 0;
;     }
;   }
;   return t;
; }
; __device__ __forceinline__ void tr_load(const Params& p, char* ws, int job, int tid, float4 (&r)[4]) {
;   TrJob t = tr_decode(p, ws, job);
;   const int c4 = tid & 15, rr = tid >> 4;
;   const float* s0 = t.src + (size_t)(t.kt * 64 + rr) * t.N + t.nt * 64 + c4 * 4;
; #pragma unroll
;   for (int pp = 0; pp < 4; ++pp) {
;     f32x4 v_ = __builtin_nontemporal_load((const f32x4*)(s0 + (size_t)(16 * pp) * t.N));
;     r[pp] = make_float4(v_[0], v_[1], v_[2], v_[3]);
;   }
; }
.Ltr_p5l0_dec_done:
	s_mul_i32 s85, s80, s82
	s_lshl_b32 s85, s85, 8
	s_lshl_b32 s79, s81, 8
	s_add_u32 s85, s85, s79
	s_add_u32 s90, s86, s85
	s_addc_u32 s91, s87, 0
	s_lshl_b32 s92, s82, 2
	s_lshl_b32 s93, s82, 6
	v_mad_u32_u24 v240, v242, s92, v241
	global_load_dwordx4 v[212:215], v240, s[90:91] nt
	v_add_u32_e32 v211, s93, v240
	global_load_dwordx4 v[216:219], v211, s[90:91] nt
	v_add_u32_e32 v240, s93, v211
	global_load_dwordx4 v[220:223], v240, s[90:91] nt
	v_add_u32_e32 v211, s93, v240
	global_load_dwordx4 v[224:227], v211, s[90:91] nt
	s_add_u32 s76, s76, 448
	s_min_u32 s78, s76, 37247
	s_cmp_ge_u32 s78, 25472
	s_cselect_b32 s79, 1, 0
	s_cselect_b32 s85, 25472, 0
	s_sub_u32 s78, s78, s85
	s_cmp_lt_u32 s78, 640
	s_cbranch_scc0 .Ltr_p5l1_notin
	s_mul_hi_u32 s80, s78, 107374183
	s_mul_i32 s85, s80, 40
	s_sub_u32 s81, s78, s85
	s_movk_i32 s82, 2560
	s_movk_i32 s83, 1024
	s_mov_b32 s84, -1
	s_mul_i32 s85, s79, 10485760
	s_add_u32 s86, s64, s85
	s_addc_u32 s87, s65, 0
	s_mul_i32 s85, s79, 5242880
	s_add_u32 s88, s74, s85
	s_addc_u32 s89, s75, 0
	s_branch .Ltr_p5l1_dec_done

; __device__ __forceinline__ void tr_load(const Params& p, char* ws, int job, int tid, float4 (&r)[4]) {
;   TrJob t = tr_decode(p, ws, job);
;   const int c4 = tid & 15, rr = tid >> 4;
;   const float* s0 = t.src + (size_t)(t.kt * 64 + rr) * t.N + t.nt * 64 + c4 * 4;
; #pragma unroll
;   for (int pp = 0; pp < 4; ++pp) {
;     f32x4 v_ = __builtin_nontemporal_load((const f32x4*)(s0 + (size_t)(16 * pp) * t.N));
;     r[pp] = make_float4(v_[0], v_[1], v_[2], v_[3]);
;   }
; }
; __device__ __forceinline__ void tr_lds_write(float* tile, int tid, const float4 (&r)[4]) {
;   const int c4 = tid & 15, rr = tid >> 4;
; #pragma unroll
;   for (int pp = 0; pp < 4; ++pp) {
;     float* t = &tile[(rr + 16 * pp) * 65 + c4 * 4];
;     t[0] = r[pp].x; t[1] = r[pp].y; t[2] = r[pp].z; t[3] = r[pp].w;
;   }
; }
; __device__ __forceinline__ void tr_store(const Params& p, char* ws, int job, int tid, const float* tile) {
;   TrJob t = tr_decode(p, ws, job);
;   const int kc = tid & 7, nn = tid >> 3;
; #pragma unroll
;   for (int pp = 0; pp < 2; ++pp) {
;     int n = nn + 32 * pp;
;     float v[8];
; #pragma unroll
;     for (int j = 0; j < 8; ++j) v[j] = tile[(kc * 8 + j) * 65 + n];
.Ltr_p5l1_dec_done:
	s_mul_i32 s85, s80, s82
	s_lshl_b32 s85, s85, 8
	s_lshl_b32 s79, s81, 8
	s_add_u32 s85, s85, s79
	s_add_u32 s90, s86, s85
	s_addc_u32 s91, s87, 0
	s_lshl_b32 s92, s82, 2
	s_lshl_b32 s93, s82, 6
	v_mad_u32_u24 v240, v242, s92, v241
	global_load_dwordx4 v[228:231], v240, s[90:91] nt
	v_add_u32_e32 v211, s93, v240
	global_load_dwordx4 v[232:235], v211, s[90:91] nt
	v_add_u32_e32 v240, s93, v211
	global_load_dwordx4 v[186:189], v240, s[90:91] nt
	v_add_u32_e32 v211, s93, v240
	global_load_dwordx4 v[190:193], v211, s[90:91] nt
	s_add_u32 s76, s76, 448
	s_sub_u32 s76, s76, 896
	s_waitcnt vmcnt(0)
	v_add_u32_e32 v247, s96, v243
	ds_write_b32 v247, v212 offset:0
	ds_write_b32 v247, v213 offset:4
	ds_write_b32 v247, v214 offset:8
	ds_write_b32 v247, v215 offset:12
	ds_write_b32 v247, v216 offset:4160
	ds_write_b32 v247, v217 offset:4164
	ds_write_b32 v247, v218 offset:4168
	ds_write_b32 v247, v219 offset:4172
	ds_write_b32 v247, v220 offset:8320
	ds_write_b32 v247, v221 offset:8324
	ds_write_b32 v247, v222 offset:8328
	ds_write_b32 v247, v223 offset:8332
	ds_write_b32 v247, v224 offset:12480
	ds_write_b32 v247, v225 offset:12484
	ds_write_b32 v247, v226 offset:12488
	ds_write_b32 v247, v227 offset:12492
	v_add_u32_e32 v247, s96, v244
	s_waitcnt lgkmcnt(0)
	s_barrier
	ds_read_b32 v212, v247 offset:0
	ds_read_b32 v213, v247 offset:260
	ds_read_b32 v214, v247 offset:520
	ds_read_b32 v215, v247 offset:780
	ds_read_b32 v216, v247 offset:1040
	ds_read_b32 v217, v247 offset:1300
	ds_read_b32 v218, v247 offset:1560
	ds_read_b32 v219, v247 offset:1820
	ds_read_b32 v220, v247 offset:128
	ds_read_b32 v221, v247 offset:388
	ds_read_b32 v222, v247 offset:648
	ds_read_b32 v223, v247 offset:908
	ds_read_b32 v224, v247 offset:1168
	ds_read_b32 v225, v247 offset:1428
	ds_read_b32 v226, v247 offset:1688
	ds_read_b32 v227, v247 offset:1948
	s_min_u32 s78, s76, 37247
	s_cmp_ge_u32 s78, 25472
	s_cselect_b32 s79, 1, 0
	s_cselect_b32 s85, 25472, 0
	s_sub_u32 s78, s78, s85
	s_cmp_lt_u32 s78, 640
	s_cbranch_scc0 .Ltr_p5s0_notin
	s_mul_hi_u32 s80, s78, 107374183
	s_mul_i32 s85, s80, 40
	s_sub_u32 s81, s78, s85
	s_movk_i32 s82, 2560
	s_movk_i32 s83, 1024
	s_mov_b32 s84, -1
	s_mul_i32 s85, s79, 10485760
	s_add_u32 s86, s64, s85
	s_addc_u32 s87, s65, 0
	s_mul_i32 s85, s79, 5242880
	s_add_u32 s88, s74, s85
	s_addc_u32 s89, s75, 0
	s_branch .Ltr_p5s0_dec_done

; __device__ __forceinline__ unsigned pack2(float a, float b) { return (unsigned)f2bf(a) | ((unsigned)f2bf(b) << 16); }
; __device__ __forceinline__ void tr_lds_write(float* tile, int tid, const float4 (&r)[4]) {
;   const int c4 = tid & 15, rr = tid >> 4;
; #pragma unroll
;   for (int pp = 0; pp < 4; ++pp) {
;     float* t = &tile[(rr + 16 * pp) * 65 + c4 * 4];
;     t[0] = r[pp].x; t[1] = r[pp].y; t[2] = r[pp].z; t[3] = r[pp].w;
;   }
; }
; __device__ __forceinline__ void tr_store(const Params& p, char* ws, int job, int tid, const float* tile) {
;   TrJob t = tr_decode(p, ws, job);
;   const int kc = tid & 7, nn = tid >> 3;
; #pragma unroll
;   for (int pp = 0; pp < 2; ++pp) {
;     int n = nn + 32 * pp;
;     float v[8];
; #pragma unroll
;     for (int j = 0; j < 8; ++j) v[j] = tile[(kc * 8 + j) * 65 + n];
;     uint4 o;
;     o.x = pack2(v[0], v[1]); o.y = pack2(v[2], v[3]); o.z = pack2(v[4], v[5]); o.w = pack2(v[6], v[7]);
;     int gn = t.nt * 64 + n;
;     int drow = t.mode == 0 ? gn : gu_row(t.mode - 1, gn);
;     *(uint4*)&t.dst[(size_t)drow * t.K + t.kt * 64 + kc * 8] = o;
;   }
; }
.Ltr_p5s0_dec_done:
	s_lshl_b32 s97, s83, 1
	s_cmp_eq_u32 s84, -1
	s_cselect_b32 s79, 6, 7
	s_cselect_b32 s85, 32, 64
	s_cselect_b32 s78, 0, s84
	s_lshl_b32 s79, s81, s79
	s_add_u32 s79, s79, s78
	s_add_u32 s85, s85, s79
	s_mul_i32 s79, s79, s97
	s_mul_i32 s85, s85, s97
	s_lshl_b32 s78, s80, 7
	s_add_u32 s79, s79, s78
	s_add_u32 s85, s85, s78
	s_add_u32 s94, s88, s79
	s_addc_u32 s95, s89, 0
	s_add_u32 s98, s88, s85
	s_addc_u32 s99, s89, 0
	v_mad_u32_u24 v254, v245, s97, v246
	s_movk_i32 s78, 0x7fff
	s_mov_b32 s79, 0xffff0000
	s_waitcnt lgkmcnt(0)
	v_bfe_u32 v252, v212, 16, 1
	v_bfe_u32 v253, v213, 16, 1
	v_add3_u32 v252, v212, v252, s78
	v_add3_u32 v253, v213, v253, s78
	v_lshrrev_b32_e32 v252, 16, v252
	v_and_or_b32 v248, v253, s79, v252
	v_bfe_u32 v252, v214, 16, 1
	v_bfe_u32 v253, v215, 16, 1
	v_add3_u32 v252, v214, v252, s78
	v_add3_u32 v253, v215, v253, s78
	v_lshrrev_b32_e32 v252, 16, v252
	v_and_or_b32 v249, v253, s79, v252
	v_bfe_u32 v252, v216, 16, 1
	v_bfe_u32 v253, v217, 16, 1
	v_add3_u32 v252, v216, v252, s78
	v_add3_u32 v253, v217, v253, s78
	v_lshrrev_b32_e32 v252, 16, v252
	v_and_or_b32 v250, v253, s79, v252
	v_bfe_u32 v252, v218, 16, 1
	v_bfe_u32 v253, v219, 16, 1
	v_add3_u32 v252, v218, v252, s78
	v_add3_u32 v253, v219, v253, s78
	v_lshrrev_b32_e32 v252, 16, v252
	v_and_or_b32 v251, v253, s79, v252
	global_store_dwordx4 v254, v[248:251], s[94:95]
	s_nop 1
	v_bfe_u32 v252, v220, 16, 1
	v_bfe_u32 v253, v221, 16, 1
	v_add3_u32 v252, v220, v252, s78
	v_add3_u32 v253, v221, v253, s78
	v_lshrrev_b32_e32 v252, 16, v252
	v_and_or_b32 v248, v253, s79, v252
	v_bfe_u32 v252, v222, 16, 1
	v_bfe_u32 v253, v223, 16, 1
	v_add3_u32 v252, v222, v252, s78
	v_add3_u32 v253, v223, v253, s78
	v_lshrrev_b32_e32 v252, 16, v252
	v_and_or_b32 v249, v253, s79, v252
	v_bfe_u32 v252, v224, 16, 1
	v_bfe_u32 v253, v225, 16, 1
	v_add3_u32 v252, v224, v252, s78
	v_add3_u32 v253, v225, v253, s78
	v_lshrrev_b32_e32 v252, 16, v252
	v_and_or_b32 v250, v253, s79, v252
	v_bfe_u32 v252, v226, 16, 1
	v_bfe_u32 v253, v227, 16, 1
	v_add3_u32 v252, v226, v252, s78
	v_add3_u32 v253, v227, v253, s78
	v_lshrrev_b32_e32 v252, 16, v252
	v_and_or_b32 v251, v253, s79, v252
	global_store_dwordx4 v254, v[248:251], s[98:99]
	s_xor_b32 s96, s96, 0x4100
	s_add_u32 s76, s76, 448
	v_add_u32_e32 v247, s96, v243
	ds_write_b32 v247, v228 offset:0
	ds_write_b32 v247, v229 offset:4
	ds_write_b32 v247, v230 offset:8
	ds_write_b32 v247, v231 offset:12
	ds_write_b32 v247, v232 offset:4160
	ds_write_b32 v247, v233 offset:4164
	ds_write_b32 v247, v234 offset:4168
	ds_write_b32 v247, v235 offset:4172
	ds_write_b32 v247, v186 offset:8320
	ds_write_b32 v247, v187 offset:8324
	ds_write_b32 v247, v188 offset:8328
	ds_write_b32 v247, v189 offset:8332
	ds_write_b32 v247, v190 offset:12480
	ds_write_b32 v247, v191 offset:12484
	ds_write_b32 v247, v192 offset:12488
	ds_write_b32 v247, v193 offset:12492
	v_add_u32_e32 v247, s96, v244
	s_waitcnt lgkmcnt(0)
	s_barrier
	ds_read_b32 v228, v247 offset:0
	ds_read_b32 v229, v247 offset:260
	ds_read_b32 v230, v247 offset:520
	ds_read_b32 v231, v247 offset:780
	ds_read_b32 v232, v247 offset:1040
	ds_read_b32 v233, v247 offset:1300
	ds_read_b32 v234, v247 offset:1560
	ds_read_b32 v235, v247 offset:1820
	ds_read_b32 v186, v247 offset:128
	ds_read_b32 v187, v247 offset:388
	ds_read_b32 v188, v247 offset:648
	ds_read_b32 v189, v247 offset:908
	ds_read_b32 v190, v247 offset:1168
	ds_read_b32 v191, v247 offset:1428
	ds_read_b32 v192, v247 offset:1688
	ds_read_b32 v193, v247 offset:1948
	s_min_u32 s78, s76, 37247
	s_cmp_ge_u32 s78, 25472
	s_cselect_b32 s79, 1, 0
	s_cselect_b32 s85, 25472, 0
	s_sub_u32 s78, s78, s85
	s_cmp_lt_u32 s78, 640
	s_cbranch_scc0 .Ltr_p5s1_notin
	s_mul_hi_u32 s80, s78, 107374183
	s_mul_i32 s85, s80, 40
	s_sub_u32 s81, s78, s85
	s_movk_i32 s82, 2560
	s_movk_i32 s83, 1024
	s_mov_b32 s84, -1
	s_mul_i32 s85, s79, 10485760
	s_add_u32 s86, s64, s85
	s_addc_u32 s87, s65, 0
	s_mul_i32 s85, s79, 5242880
	s_add_u32 s88, s74, s85
	s_addc_u32 s89, s75, 0
	s_branch .Ltr_p5s1_dec_done

; #define LAUNDER(v) asm volatile("" : "+s"(v))
; __device__ __forceinline__ int vtid() { int t = threadIdx.x; asm volatile("" : "+v"(t)); return t; }
; __device__ __forceinline__ unsigned pack2(float a, float b) { return (unsigned)f2bf(a) | ((unsigned)f2bf(b) << 16); }
; __device__ __forceinline__ void tr_store(const Params& p, char* ws, int job, int tid, const float* tile) {
;   TrJob t = tr_decode(p, ws, job);
;   const int kc = tid & 7, nn = tid >> 3;
; #pragma unroll
;   for (int pp = 0; pp < 2; ++pp) {
;     int n = nn + 32 * pp;
;     float v[8];
; #pragma unroll
;     for (int j = 0; j < 8; ++j) v[j] = tile[(kc * 8 + j) * 65 + n];
;     uint4 o;
;     o.x = pack2(v[0], v[1]); o.y = pack2(v[2], v[3]); o.z = pack2(v[4], v[5]); o.w = pack2(v[6], v[7]);
;     int gn = t.nt * 64 + n;
;     int drow = t.mode == 0 ? gn : gu_row(t.mode - 1, gn);
;     *(uint4*)&t.dst[(size_t)drow * t.K + t.kt * 64 + kc * 8] = o;
;   }
; }
; __device__ __forceinline__ void p0_transposes(const Params& p, char* smem, int bid, int nb, int jlo, int jhi) {
;   const int tid = vtid();
;   char* ws = p.ws;
;   LAUNDER(ws);
;   float* tileA = (float*)smem;
;   float* tileB = tileA + 64 * 65;
;   float4 c0[4], c1[4], n0[4], n1[4];
;   int j = jlo + bid * 2;
;   if (j < jhi) { tr_load(p, ws, j, tid, c0); tr_load(p, ws, j + 1, tid, c1); }
;   for (; j < jhi; j += 2 * nb) {
;     const int jn = j + 2 * nb;
;     if (jn < jhi) { tr_load(p, ws, jn, tid, n0); tr_load(p, ws, jn + 1, tid, n1); }
;     tr_lds_write(tileA, tid, c0);
;     tr_lds_write(tileB, tid, c1);
;     __syncthreads();
;     tr_store(p, ws, j, tid, tileA);
;     tr_store(p, ws, j + 1, tid, tileB);
;     __syncthreads();
; #pragma unroll
;     for (int q = 0; q < 4; ++q) { c0[q] = n0[q]; c1[q] = n1[q]; }
;   }
.Ltr_p5s1_dec_done:
	s_lshl_b32 s97, s83, 1
	s_cmp_eq_u32 s84, -1
	s_cselect_b32 s79, 6, 7
	s_cselect_b32 s85, 32, 64
	s_cselect_b32 s78, 0, s84
	s_lshl_b32 s79, s81, s79
	s_add_u32 s79, s79, s78
	s_add_u32 s85, s85, s79
	s_mul_i32 s79, s79, s97
	s_mul_i32 s85, s85, s97
	s_lshl_b32 s78, s80, 7
	s_add_u32 s79, s79, s78
	s_add_u32 s85, s85, s78
	s_add_u32 s94, s88, s79
	s_addc_u32 s95, s89, 0
	s_add_u32 s98, s88, s85
	s_addc_u32 s99, s89, 0
	v_mad_u32_u24 v254, v245, s97, v246
	s_movk_i32 s78, 0x7fff
	s_mov_b32 s79, 0xffff0000
	s_waitcnt lgkmcnt(0)
	v_bfe_u32 v252, v228, 16, 1
	v_bfe_u32 v253, v229, 16, 1
	v_add3_u32 v252, v228, v252, s78
	v_add3_u32 v253, v229, v253, s78
	v_lshrrev_b32_e32 v252, 16, v252
	v_and_or_b32 v248, v253, s79, v252
	v_bfe_u32 v252, v230, 16, 1
	v_bfe_u32 v253, v231, 16, 1
	v_add3_u32 v252, v230, v252, s78
	v_add3_u32 v253, v231, v253, s78
	v_lshrrev_b32_e32 v252, 16, v252
	v_and_or_b32 v249, v253, s79, v252
	v_bfe_u32 v252, v232, 16, 1
	v_bfe_u32 v253, v233, 16, 1
	v_add3_u32 v252, v232, v252, s78
	v_add3_u32 v253, v233, v253, s78
	v_lshrrev_b32_e32 v252, 16, v252
	v_and_or_b32 v250, v253, s79, v252
	v_bfe_u32 v252, v234, 16, 1
	v_bfe_u32 v253, v235, 16, 1
	v_add3_u32 v252, v234, v252, s78
	v_add3_u32 v253, v235, v253, s78
	v_lshrrev_b32_e32 v252, 16, v252
	v_and_or_b32 v251, v253, s79, v252
	global_store_dwordx4 v254, v[248:251], s[94:95]
	s_nop 1
	v_bfe_u32 v252, v186, 16, 1
	v_bfe_u32 v253, v187, 16, 1
	v_add3_u32 v252, v186, v252, s78
	v_add3_u32 v253, v187, v253, s78
	v_lshrrev_b32_e32 v252, 16, v252
	v_and_or_b32 v248, v253, s79, v252
	v_bfe_u32 v252, v188, 16, 1
	v_bfe_u32 v253, v189, 16, 1
	v_add3_u32 v252, v188, v252, s78
	v_add3_u32 v253, v189, v253, s78
	v_lshrrev_b32_e32 v252, 16, v252
	v_and_or_b32 v249, v253, s79, v252
	v_bfe_u32 v252, v190, 16, 1
	v_bfe_u32 v253, v191, 16, 1
	v_add3_u32 v252, v190, v252, s78
	v_add3_u32 v253, v191, v253, s78
	v_lshrrev_b32_e32 v252, 16, v252
	v_and_or_b32 v250, v253, s79, v252
	v_bfe_u32 v252, v192, 16, 1
	v_bfe_u32 v253, v193, 16, 1
	v_add3_u32 v252, v192, v252, s78
	v_add3_u32 v253, v193, v253, s78
	v_lshrrev_b32_e32 v252, 16, v252
	v_and_or_b32 v251, v253, s79, v252
	global_store_dwordx4 v254, v[248:251], s[98:99]
	s_xor_b32 s96, s96, 0x4100
	s_add_u32 s76, s76, 448
	s_sub_u32 s77, s77, 1
	s_cmp_lg_u32 s77, 0
	s_cbranch_scc1 .Ltrp5_batch
	s_waitcnt vmcnt(0) lgkmcnt(0)
	s_barrier
	v_readlane_b32 s64, v255, 0
	v_readlane_b32 s65, v255, 1
	v_readlane_b32 s66, v255, 2
	v_readlane_b32 s67, v255, 3
	v_readlane_b32 s68, v255, 4
	v_readlane_b32 s69, v255, 5
	v_readlane_b32 s70, v255, 6
	v_readlane_b32 s71, v255, 7
	v_readlane_b32 s72, v255, 8
	v_readlane_b32 s73, v255, 9
	v_readlane_b32 s74, v255, 10
	v_readlane_b32 s75, v255, 11
	v_readlane_b32 s76, v255, 12
	v_readlane_b32 s77, v255, 13
	v_readlane_b32 s78, v255, 14
	v_readlane_b32 s79, v255, 15
	v_readlane_b32 s80, v255, 16
	v_readlane_b32 s81, v255, 17
	v_readlane_b32 s82, v255, 18
	v_readlane_b32 s83, v255, 19
	v_readlane_b32 s84, v255, 20
	v_readlane_b32 s85, v255, 21
	v_readlane_b32 s86, v255, 22
	v_readlane_b32 s87, v255, 23
	v_readlane_b32 s88, v255, 24
	v_readlane_b32 s89, v255, 25
	v_readlane_b32 s90, v255, 26
	v_readlane_b32 s91, v255, 27
	v_readlane_b32 s92, v255, 28
	v_readlane_b32 s93, v255, 29
	v_readlane_b32 s94, v255, 30
	v_readlane_b32 s95, v255, 31
	v_readlane_b32 s96, v255, 32
	v_readlane_b32 s97, v255, 33
	v_readlane_b32 s98, v255, 34
	v_readlane_b32 s99, v255, 35
	v_readlane_b32 vcc_lo, v255, 36
	v_readlane_b32 vcc_hi, v255, 37
	s_nop 4

; #define GSYNC() do { xcd_barrier(xb); if (REP_MASK & 256) xcd_barrier(xb); } while (0)
; #define LAUNDER(v) asm volatile("" : "+s"(v))
; __device__ __forceinline__ int vtid() { int t = threadIdx.x; asm volatile("" : "+v"(t)); return t; }
; __device__ __forceinline__ void p0_transposes(const Params& p, char* smem, int bid, int nb, int jlo, int jhi) {
;   const int tid = vtid();
;   char* ws = p.ws;
;   LAUNDER(ws);
;   float* tileA = (float*)smem;
;   float* tileB = tileA + 64 * 65;
;   float4 c0[4], c1[4], n0[4], n1[4];
;   int j = jlo + bid * 2;
;   if (j < jhi) { tr_load(p, ws, j, tid, c0); tr_load(p, ws, j + 1, tid, c1); }
;   for (; j < jhi; j += 2 * nb) {
; __global__ void __launch_bounds__(256, 2) fwd_megakernel(Params p) {
;     ...
;     if (l == 0) {
;       for (int job = bid; job < 264; job += nb) norm_job(p, 1, job, false);
;       GSYNC();
.LBB0_2017:
	v_readlane_b32 s0, v237, 25
	v_readlane_b32 s1, v237, 26
	s_andn2_b64 vcc, exec, s[0:1]
	v_readlane_b32 s0, v238, 37
	v_readlane_b32 s2, v239, 0
	s_cbranch_vccz .LBB0_2022
	v_readlane_b32 s100, v236, 62
	v_readlane_b32 s101, v236, 63
	v_writelane_b32 v255, s64, 0
	v_writelane_b32 v255, s65, 1
	v_writelane_b32 v255, s66, 2
	v_writelane_b32 v255, s67, 3
	v_writelane_b32 v255, s68, 4
	v_writelane_b32 v255, s69, 5
	v_writelane_b32 v255, s70, 6
	v_writelane_b32 v255, s71, 7
	v_writelane_b32 v255, s72, 8
	v_writelane_b32 v255, s73, 9
	v_writelane_b32 v255, s74, 10
	v_writelane_b32 v255, s75, 11
	v_writelane_b32 v255, s76, 12
	v_writelane_b32 v255, s77, 13
	v_writelane_b32 v255, s78, 14
	v_writelane_b32 v255, s79, 15
	v_writelane_b32 v255, s80, 16
	v_writelane_b32 v255, s81, 17
	v_writelane_b32 v255, s82, 18
	v_writelane_b32 v255, s83, 19
	v_writelane_b32 v255, s84, 20
	v_writelane_b32 v255, s85, 21
	v_writelane_b32 v255, s86, 22
	v_writelane_b32 v255, s87, 23
	v_writelane_b32 v255, s88, 24
	v_writelane_b32 v255, s89, 25
	v_writelane_b32 v255, s90, 26
	v_writelane_b32 v255, s91, 27
	v_writelane_b32 v255, s92, 28
	v_writelane_b32 v255, s93, 29
	v_writelane_b32 v255, s94, 30
	v_writelane_b32 v255, s95, 31
	v_writelane_b32 v255, s96, 32
	v_writelane_b32 v255, s97, 33
	v_writelane_b32 v255, s98, 34
	v_writelane_b32 v255, s99, 35
	v_writelane_b32 v255, vcc_lo, 36
	v_writelane_b32 v255, vcc_hi, 37
	s_load_dwordx4 s[64:67], s[100:101], 0x40
	s_load_dwordx4 s[68:71], s[100:101], 0xc8
	s_load_dwordx2 s[72:73], s[100:101], 0xd8
	s_load_dwordx2 s[74:75], s[100:101], 0xe8
	v_and_b32_e32 v241, 15, v172
	v_lshrrev_b32_e32 v242, 4, v172
	v_lshlrev_b32_e32 v241, 4, v241
	v_mul_u32_u24_e32 v243, 0x104, v242
	v_add_u32_e32 v243, v243, v241
	v_and_b32_e32 v246, 7, v172
	v_lshrrev_b32_e32 v245, 3, v172
	v_mul_u32_u24_e32 v244, 0x820, v246
	v_lshl_add_u32 v244, v245, 2, v244
	v_lshlrev_b32_e32 v246, 4, v246
	v_readlane_b32 s76, v239, 0
	s_add_u32 s76, s76, 33704
	s_movk_i32 s77, 3
	s_mov_b32 s96, 0
	s_waitcnt lgkmcnt(0)
.Ltrp8_batch:
	s_min_u32 s78, s76, 35455
	s_cmp_ge_u32 s78, 25472
	s_cselect_b32 s79, 1, 0
	s_cselect_b32 s85, 25472, 0
	s_sub_u32 s78, s78, s85
	s_cmp_lt_u32 s78, 640
	s_cbranch_scc0 .Ltr_p8l0_notin
	s_mul_hi_u32 s80, s78, 107374183
	s_mul_i32 s85, s80, 40
	s_sub_u32 s81, s78, s85
	s_movk_i32 s82, 2560
	s_movk_i32 s83, 1024
	s_mov_b32 s84, -1
	s_mul_i32 s85, s79, 10485760
	s_add_u32 s86, s64, s85
	s_addc_u32 s87, s65, 0
	s_mul_i32 s85, s79, 5242880
	s_add_u32 s88, s74, s85
	s_addc_u32 s89, s75, 0
	s_branch .Ltr_p8l0_dec_done

; __device__ __forceinline__ TrJob tr_decode(const Params& p, char* ws, int job) {
;   TrJob t;
;   int l = job / TJ_PER_LAYER, rj = job % TJ_PER_LAYER;
;   if (rj < 640) {
;     t.src = p.w_in + (size_t)l * 1024 * 2560; t.K = 1024; t.N = 2560; t.kt = rj / 40; t.nt = rj % 40;
;     t.dst = (u16*)(ws + OFF_WINT) + (size_t)l * 2560 * 1024; t.mode = 0;
; __device__ __forceinline__ void tr_load(const Params& p, char* ws, int job, int tid, float4 (&r)[4]) {
;   TrJob t = tr_decode(p, ws, job);
;   const int c4 = tid & 15, rr = tid >> 4;
;   const float* s0 = t.src + (size_t)(t.kt * 64 + rr) * t.N + t.nt * 64 + c4 * 4;
; #pragma unroll
;   for (int pp = 0; pp < 4; ++pp) {
;     f32x4 v_ = __builtin_nontemporal_load((const f32x4*)(s0 + (size_t)(16 * pp) * t.N));
;     r[pp] = make_float4(v_[0], v_[1], v_[2], v_[3]);
;   }
; }
.Ltr_p8l0_dec_done:
	s_mul_i32 s85, s80, s82
	s_lshl_b32 s85, s85, 8
	s_lshl_b32 s79, s81, 8
	s_add_u32 s85, s85, s79
	s_add_u32 s90, s86, s85
	s_addc_u32 s91, s87, 0
	s_lshl_b32 s92, s82, 2
	s_lshl_b32 s93, s82, 6
	v_mad_u32_u24 v240, v242, s92, v241
	global_load_dwordx4 v[212:215], v240, s[90:91] nt
	v_add_u32_e32 v211, s93, v240
	global_load_dwordx4 v[216:219], v211, s[90:91] nt
	v_add_u32_e32 v240, s93, v211
	global_load_dwordx4 v[220:223], v240, s[90:91] nt
	v_add_u32_e32 v211, s93, v240
	global_load_dwordx4 v[224:227], v211, s[90:91] nt
	s_add_u32 s76, s76, 248
	s_min_u32 s78, s76, 35455
	s_cmp_ge_u32 s78, 25472
	s_cselect_b32 s79, 1, 0
	s_cselect_b32 s85, 25472, 0
	s_sub_u32 s78, s78, s85
	s_cmp_lt_u32 s78, 640
	s_cbranch_scc0 .Ltr_p8l1_notin
	s_mul_hi_u32 s80, s78, 107374183
	s_mul_i32 s85, s80, 40
	s_sub_u32 s81, s78, s85
	s_movk_i32 s82, 2560
	s_movk_i32 s83, 1024
	s_mov_b32 s84, -1
	s_mul_i32 s85, s79, 10485760
	s_add_u32 s86, s64, s85
	s_addc_u32 s87, s65, 0
	s_mul_i32 s85, s79, 5242880
	s_add_u32 s88, s74, s85
	s_addc_u32 s89, s75, 0
	s_branch .Ltr_p8l1_dec_done

; __device__ __forceinline__ void tr_load(const Params& p, char* ws, int job, int tid, float4 (&r)[4]) {
;   TrJob t = tr_decode(p, ws, job);
;   const int c4 = tid & 15, rr = tid >> 4;
;   const float* s0 = t.src + (size_t)(t.kt * 64 + rr) * t.N + t.nt * 64 + c4 * 4;
; #pragma unroll
;   for (int pp = 0; pp < 4; ++pp) {
;     f32x4 v_ = __builtin_nontemporal_load((const f32x4*)(s0 + (size_t)(16 * pp) * t.N));
;     r[pp] = make_float4(v_[0], v_[1], v_[2], v_[3]);
;   }
; }
; __device__ __forceinline__ void tr_lds_write(float* tile, int tid, const float4 (&r)[4]) {
;   const int c4 = tid & 15, rr = tid >> 4;
; #pragma unroll
;   for (int pp = 0; pp < 4; ++pp) {
;     float* t = &tile[(rr + 16 * pp) * 65 + c4 * 4];
;     t[0] = r[pp].x; t[1] = r[pp].y; t[2] = r[pp].z; t[3] = r[pp].w;
;   }
; }
; __device__ __forceinline__ void tr_store(const Params& p, char* ws, int job, int tid, const float* tile) {
;   TrJob t = tr_decode(p, ws, job);
;   const int kc = tid & 7, nn = tid >> 3;
; #pragma unroll
;   for (int pp = 0; pp < 2; ++pp) {
;     int n = nn + 32 * pp;
;     float v[8];
; #pragma unroll
;     for (int j = 0; j < 8; ++j) v[j] = tile[(kc * 8 + j) * 65 + n];
.Ltr_p8l1_dec_done:
	s_mul_i32 s85, s80, s82
	s_lshl_b32 s85, s85, 8
	s_lshl_b32 s79, s81, 8
	s_add_u32 s85, s85, s79
	s_add_u32 s90, s86, s85
	s_addc_u32 s91, s87, 0
	s_lshl_b32 s92, s82, 2
	s_lshl_b32 s93, s82, 6
	v_mad_u32_u24 v240, v242, s92, v241
	global_load_dwordx4 v[228:231], v240, s[90:91] nt
	v_add_u32_e32 v211, s93, v240
	global_load_dwordx4 v[232:235], v211, s[90:91] nt
	v_add_u32_e32 v240, s93, v211
	global_load_dwordx4 v[186:189], v240, s[90:91] nt
	v_add_u32_e32 v211, s93, v240
	global_load_dwordx4 v[190:193], v211, s[90:91] nt
	s_add_u32 s76, s76, 248
	s_sub_u32 s76, s76, 496
	s_waitcnt vmcnt(0)
	v_add_u32_e32 v247, s96, v243
	ds_write_b32 v247, v212 offset:0
	ds_write_b32 v247, v213 offset:4
	ds_write_b32 v247, v214 offset:8
	ds_write_b32 v247, v215 offset:12
	ds_write_b32 v247, v216 offset:4160
	ds_write_b32 v247, v217 offset:4164
	ds_write_b32 v247, v218 offset:4168
	ds_write_b32 v247, v219 offset:4172
	ds_write_b32 v247, v220 offset:8320
	ds_write_b32 v247, v221 offset:8324
	ds_write_b32 v247, v222 offset:8328
	ds_write_b32 v247, v223 offset:8332
	ds_write_b32 v247, v224 offset:12480
	ds_write_b32 v247, v225 offset:12484
	ds_write_b32 v247, v226 offset:12488
	ds_write_b32 v247, v227 offset:12492
	v_add_u32_e32 v247, s96, v244
	s_waitcnt lgkmcnt(0)
	s_barrier
	ds_read_b32 v212, v247 offset:0
	ds_read_b32 v213, v247 offset:260
	ds_read_b32 v214, v247 offset:520
	ds_read_b32 v215, v247 offset:780
	ds_read_b32 v216, v247 offset:1040
	ds_read_b32 v217, v247 offset:1300
	ds_read_b32 v218, v247 offset:1560
	ds_read_b32 v219, v247 offset:1820
	ds_read_b32 v220, v247 offset:128
	ds_read_b32 v221, v247 offset:388
	ds_read_b32 v222, v247 offset:648
	ds_read_b32 v223, v247 offset:908
	ds_read_b32 v224, v247 offset:1168
	ds_read_b32 v225, v247 offset:1428
	ds_read_b32 v226, v247 offset:1688
	ds_read_b32 v227, v247 offset:1948
	s_min_u32 s78, s76, 35455
	s_cmp_ge_u32 s78, 25472
	s_cselect_b32 s79, 1, 0
	s_cselect_b32 s85, 25472, 0
	s_sub_u32 s78, s78, s85
	s_cmp_lt_u32 s78, 640
	s_cbranch_scc0 .Ltr_p8s0_notin
	s_mul_hi_u32 s80, s78, 107374183
	s_mul_i32 s85, s80, 40
	s_sub_u32 s81, s78, s85
	s_movk_i32 s82, 2560
	s_movk_i32 s83, 1024
	s_mov_b32 s84, -1
	s_mul_i32 s85, s79, 10485760
	s_add_u32 s86, s64, s85
	s_addc_u32 s87, s65, 0
	s_mul_i32 s85, s79, 5242880
	s_add_u32 s88, s74, s85
	s_addc_u32 s89, s75, 0
	s_branch .Ltr_p8s0_dec_done

; __device__ __forceinline__ unsigned pack2(float a, float b) { return (unsigned)f2bf(a) | ((unsigned)f2bf(b) << 16); }
; __device__ __forceinline__ void tr_lds_write(float* tile, int tid, const float4 (&r)[4]) {
;   const int c4 = tid & 15, rr = tid >> 4;
; #pragma unroll
;   for (int pp = 0; pp < 4; ++pp) {
;     float* t = &tile[(rr + 16 * pp) * 65 + c4 * 4];
;     t[0] = r[pp].x; t[1] = r[pp].y; t[2] = r[pp].z; t[3] = r[pp].w;
;   }
; }
; __device__ __forceinline__ void tr_store(const Params& p, char* ws, int job, int tid, const float* tile) {
;   TrJob t = tr_decode(p, ws, job);
;   const int kc = tid & 7, nn = tid >> 3;
; #pragma unroll
;   for (int pp = 0; pp < 2; ++pp) {
;     int n = nn + 32 * pp;
;     float v[8];
; #pragma unroll
;     for (int j = 0; j < 8; ++j) v[j] = tile[(kc * 8 + j) * 65 + n];
;     uint4 o;
;     o.x = pack2(v[0], v[1]); o.y = pack2(v[2], v[3]); o.z = pack2(v[4], v[5]); o.w = pack2(v[6], v[7]);
;     int gn = t.nt * 64 + n;
;     int drow = t.mode == 0 ? gn : gu_row(t.mode - 1, gn);
;     *(uint4*)&t.dst[(size_t)drow * t.K + t.kt * 64 + kc * 8] = o;
;   }
; }
.Ltr_p8s0_dec_done:
	s_lshl_b32 s97, s83, 1
	s_cmp_eq_u32 s84, -1
	s_cselect_b32 s79, 6, 7
	s_cselect_b32 s85, 32, 64
	s_cselect_b32 s78, 0, s84
	s_lshl_b32 s79, s81, s79
	s_add_u32 s79, s79, s78
	s_add_u32 s85, s85, s79
	s_mul_i32 s79, s79, s97
	s_mul_i32 s85, s85, s97
	s_lshl_b32 s78, s80, 7
	s_add_u32 s79, s79, s78
	s_add_u32 s85, s85, s78
	s_add_u32 s94, s88, s79
	s_addc_u32 s95, s89, 0
	s_add_u32 s98, s88, s85
	s_addc_u32 s99, s89, 0
	v_mad_u32_u24 v254, v245, s97, v246
	s_movk_i32 s78, 0x7fff
	s_mov_b32 s79, 0xffff0000
	s_waitcnt lgkmcnt(0)
	v_bfe_u32 v252, v212, 16, 1
	v_bfe_u32 v253, v213, 16, 1
	v_add3_u32 v252, v212, v252, s78
	v_add3_u32 v253, v213, v253, s78
	v_lshrrev_b32_e32 v252, 16, v252
	v_and_or_b32 v248, v253, s79, v252
	v_bfe_u32 v252, v214, 16, 1
	v_bfe_u32 v253, v215, 16, 1
	v_add3_u32 v252, v214, v252, s78
	v_add3_u32 v253, v215, v253, s78
	v_lshrrev_b32_e32 v252, 16, v252
	v_and_or_b32 v249, v253, s79, v252
	v_bfe_u32 v252, v216, 16, 1
	v_bfe_u32 v253, v217, 16, 1
	v_add3_u32 v252, v216, v252, s78
	v_add3_u32 v253, v217, v253, s78
	v_lshrrev_b32_e32 v252, 16, v252
	v_and_or_b32 v250, v253, s79, v252
	v_bfe_u32 v252, v218, 16, 1
	v_bfe_u32 v253, v219, 16, 1
	v_add3_u32 v252, v218, v252, s78
	v_add3_u32 v253, v219, v253, s78
	v_lshrrev_b32_e32 v252, 16, v252
	v_and_or_b32 v251, v253, s79, v252
	global_store_dwordx4 v254, v[248:251], s[94:95]
	s_nop 1
	v_bfe_u32 v252, v220, 16, 1
	v_bfe_u32 v253, v221, 16, 1
	v_add3_u32 v252, v220, v252, s78
	v_add3_u32 v253, v221, v253, s78
	v_lshrrev_b32_e32 v252, 16, v252
	v_and_or_b32 v248, v253, s79, v252
	v_bfe_u32 v252, v222, 16, 1
	v_bfe_u32 v253, v223, 16, 1
	v_add3_u32 v252, v222, v252, s78
	v_add3_u32 v253, v223, v253, s78
	v_lshrrev_b32_e32 v252, 16, v252
	v_and_or_b32 v249, v253, s79, v252
	v_bfe_u32 v252, v224, 16, 1
	v_bfe_u32 v253, v225, 16, 1
	v_add3_u32 v252, v224, v252, s78
	v_add3_u32 v253, v225, v253, s78
	v_lshrrev_b32_e32 v252, 16, v252
	v_and_or_b32 v250, v253, s79, v252
	v_bfe_u32 v252, v226, 16, 1
	v_bfe_u32 v253, v227, 16, 1
	v_add3_u32 v252, v226, v252, s78
	v_add3_u32 v253, v227, v253, s78
	v_lshrrev_b32_e32 v252, 16, v252
	v_and_or_b32 v251, v253, s79, v252
	global_store_dwordx4 v254, v[248:251], s[98:99]
	s_xor_b32 s96, s96, 0x4100
	s_add_u32 s76, s76, 248
	v_add_u32_e32 v247, s96, v243
	ds_write_b32 v247, v228 offset:0
	ds_write_b32 v247, v229 offset:4
	ds_write_b32 v247, v230 offset:8
	ds_write_b32 v247, v231 offset:12
	ds_write_b32 v247, v232 offset:4160
	ds_write_b32 v247, v233 offset:4164
	ds_write_b32 v247, v234 offset:4168
	ds_write_b32 v247, v235 offset:4172
	ds_write_b32 v247, v186 offset:8320
	ds_write_b32 v247, v187 offset:8324
	ds_write_b32 v247, v188 offset:8328
	ds_write_b32 v247, v189 offset:8332
	ds_write_b32 v247, v190 offset:12480
	ds_write_b32 v247, v191 offset:12484
	ds_write_b32 v247, v192 offset:12488
	ds_write_b32 v247, v193 offset:12492
	v_add_u32_e32 v247, s96, v244
	s_waitcnt lgkmcnt(0)
	s_barrier
	ds_read_b32 v228, v247 offset:0
	ds_read_b32 v229, v247 offset:260
	ds_read_b32 v230, v247 offset:520
	ds_read_b32 v231, v247 offset:780
	ds_read_b32 v232, v247 offset:1040
	ds_read_b32 v233, v247 offset:1300
	ds_read_b32 v234, v247 offset:1560
	ds_read_b32 v235, v247 offset:1820
	ds_read_b32 v186, v247 offset:128
	ds_read_b32 v187, v247 offset:388
	ds_read_b32 v188, v247 offset:648
	ds_read_b32 v189, v247 offset:908
	ds_read_b32 v190, v247 offset:1168
	ds_read_b32 v191, v247 offset:1428
	ds_read_b32 v192, v247 offset:1688
	ds_read_b32 v193, v247 offset:1948
	s_min_u32 s78, s76, 35455
	s_cmp_ge_u32 s78, 25472
	s_cselect_b32 s79, 1, 0
	s_cselect_b32 s85, 25472, 0
	s_sub_u32 s78, s78, s85
	s_cmp_lt_u32 s78, 640
	s_cbranch_scc0 .Ltr_p8s1_notin
	s_mul_hi_u32 s80, s78, 107374183
	s_mul_i32 s85, s80, 40
	s_sub_u32 s81, s78, s85
	s_movk_i32 s82, 2560
	s_movk_i32 s83, 1024
	s_mov_b32 s84, -1
	s_mul_i32 s85, s79, 10485760
	s_add_u32 s86, s64, s85
	s_addc_u32 s87, s65, 0
	s_mul_i32 s85, s79, 5242880
	s_add_u32 s88, s74, s85
	s_addc_u32 s89, s75, 0
	s_branch .Ltr_p8s1_dec_done

; #define LAUNDER(v) asm volatile("" : "+s"(v))
; __device__ __forceinline__ int vtid() { int t = threadIdx.x; asm volatile("" : "+v"(t)); return t; }
; __device__ __forceinline__ unsigned pack2(float a, float b) { return (unsigned)f2bf(a) | ((unsigned)f2bf(b) << 16); }
; __device__ __forceinline__ void tr_store(const Params& p, char* ws, int job, int tid, const float* tile) {
;   TrJob t = tr_decode(p, ws, job);
;   const int kc = tid & 7, nn = tid >> 3;
; #pragma unroll
;   for (int pp = 0; pp < 2; ++pp) {
;     int n = nn + 32 * pp;
;     float v[8];
; #pragma unroll
;     for (int j = 0; j < 8; ++j) v[j] = tile[(kc * 8 + j) * 65 + n];
;     uint4 o;
;     o.x = pack2(v[0], v[1]); o.y = pack2(v[2], v[3]); o.z = pack2(v[4], v[5]); o.w = pack2(v[6], v[7]);
;     int gn = t.nt * 64 + n;
;     int drow = t.mode == 0 ? gn : gu_row(t.mode - 1, gn);
;     *(uint4*)&t.dst[(size_t)drow * t.K + t.kt * 64 + kc * 8] = o;
;   }
; }
; __device__ __forceinline__ void p0_transposes(const Params& p, char* smem, int bid, int nb, int jlo, int jhi) {
;   const int tid = vtid();
;   char* ws = p.ws;
;   LAUNDER(ws);
;   float* tileA = (float*)smem;
;   float* tileB = tileA + 64 * 65;
;   float4 c0[4], c1[4], n0[4], n1[4];
;   int j = jlo + bid * 2;
;   if (j < jhi) { tr_load(p, ws, j, tid, c0); tr_load(p, ws, j + 1, tid, c1); }
;   for (; j < jhi; j += 2 * nb) {
;     const int jn = j + 2 * nb;
;     if (jn < jhi) { tr_load(p, ws, jn, tid, n0); tr_load(p, ws, jn + 1, tid, n1); }
;     tr_lds_write(tileA, tid, c0);
;     tr_lds_write(tileB, tid, c1);
;     __syncthreads();
;     tr_store(p, ws, j, tid, tileA);
;     tr_store(p, ws, j + 1, tid, tileB);
;     __syncthreads();
; #pragma unroll
;     for (int q = 0; q < 4; ++q) { c0[q] = n0[q]; c1[q] = n1[q]; }
;   }
.Ltr_p8s1_dec_done:
	s_lshl_b32 s97, s83, 1
	s_cmp_eq_u32 s84, -1
	s_cselect_b32 s79, 6, 7
	s_cselect_b32 s85, 32, 64
	s_cselect_b32 s78, 0, s84
	s_lshl_b32 s79, s81, s79
	s_add_u32 s79, s79, s78
	s_add_u32 s85, s85, s79
	s_mul_i32 s79, s79, s97
	s_mul_i32 s85, s85, s97
	s_lshl_b32 s78, s80, 7
	s_add_u32 s79, s79, s78
	s_add_u32 s85, s85, s78
	s_add_u32 s94, s88, s79
	s_addc_u32 s95, s89, 0
	s_add_u32 s98, s88, s85
	s_addc_u32 s99, s89, 0
	v_mad_u32_u24 v254, v245, s97, v246
	s_movk_i32 s78, 0x7fff
	s_mov_b32 s79, 0xffff0000
	s_waitcnt lgkmcnt(0)
	v_bfe_u32 v252, v228, 16, 1
	v_bfe_u32 v253, v229, 16, 1
	v_add3_u32 v252, v228, v252, s78
	v_add3_u32 v253, v229, v253, s78
	v_lshrrev_b32_e32 v252, 16, v252
	v_and_or_b32 v248, v253, s79, v252
	v_bfe_u32 v252, v230, 16, 1
	v_bfe_u32 v253, v231, 16, 1
	v_add3_u32 v252, v230, v252, s78
	v_add3_u32 v253, v231, v253, s78
	v_lshrrev_b32_e32 v252, 16, v252
	v_and_or_b32 v249, v253, s79, v252
	v_bfe_u32 v252, v232, 16, 1
	v_bfe_u32 v253, v233, 16, 1
	v_add3_u32 v252, v232, v252, s78
	v_add3_u32 v253, v233, v253, s78
	v_lshrrev_b32_e32 v252, 16, v252
	v_and_or_b32 v250, v253, s79, v252
	v_bfe_u32 v252, v234, 16, 1
	v_bfe_u32 v253, v235, 16, 1
	v_add3_u32 v252, v234, v252, s78
	v_add3_u32 v253, v235, v253, s78
	v_lshrrev_b32_e32 v252, 16, v252
	v_and_or_b32 v251, v253, s79, v252
	global_store_dwordx4 v254, v[248:251], s[94:95]
	s_nop 1
	v_bfe_u32 v252, v186, 16, 1
	v_bfe_u32 v253, v187, 16, 1
	v_add3_u32 v252, v186, v252, s78
	v_add3_u32 v253, v187, v253, s78
	v_lshrrev_b32_e32 v252, 16, v252
	v_and_or_b32 v248, v253, s79, v252
	v_bfe_u32 v252, v188, 16, 1
	v_bfe_u32 v253, v189, 16, 1
	v_add3_u32 v252, v188, v252, s78
	v_add3_u32 v253, v189, v253, s78
	v_lshrrev_b32_e32 v252, 16, v252
	v_and_or_b32 v249, v253, s79, v252
	v_bfe_u32 v252, v190, 16, 1
	v_bfe_u32 v253, v191, 16, 1
	v_add3_u32 v252, v190, v252, s78
	v_add3_u32 v253, v191, v253, s78
	v_lshrrev_b32_e32 v252, 16, v252
	v_and_or_b32 v250, v253, s79, v252
	v_bfe_u32 v252, v192, 16, 1
	v_bfe_u32 v253, v193, 16, 1
	v_add3_u32 v252, v192, v252, s78
	v_add3_u32 v253, v193, v253, s78
	v_lshrrev_b32_e32 v252, 16, v252
	v_and_or_b32 v251, v253, s79, v252
	global_store_dwordx4 v254, v[248:251], s[98:99]
	s_xor_b32 s96, s96, 0x4100
	s_add_u32 s76, s76, 248
	s_sub_u32 s77, s77, 1
	s_cmp_lg_u32 s77, 0
	s_cbranch_scc1 .Ltrp8_batch
	s_waitcnt vmcnt(0) lgkmcnt(0)
	s_barrier
	v_readlane_b32 s64, v255, 0
	v_readlane_b32 s65, v255, 1
	v_readlane_b32 s66, v255, 2
	v_readlane_b32 s67, v255, 3
	v_readlane_b32 s68, v255, 4
	v_readlane_b32 s69, v255, 5
	v_readlane_b32 s70, v255, 6
	v_readlane_b32 s71, v255, 7
	v_readlane_b32 s72, v255, 8
	v_readlane_b32 s73, v255, 9
	v_readlane_b32 s74, v255, 10
	v_readlane_b32 s75, v255, 11
	v_readlane_b32 s76, v255, 12
	v_readlane_b32 s77, v255, 13
	v_readlane_b32 s78, v255, 14
	v_readlane_b32 s79, v255, 15
	v_readlane_b32 s80, v255, 16
	v_readlane_b32 s81, v255, 17
	v_readlane_b32 s82, v255, 18
	v_readlane_b32 s83, v255, 19
	v_readlane_b32 s84, v255, 20
	v_readlane_b32 s85, v255, 21
	v_readlane_b32 s86, v255, 22
	v_readlane_b32 s87, v255, 23
	v_readlane_b32 s88, v255, 24
	v_readlane_b32 s89, v255, 25
	v_readlane_b32 s90, v255, 26
	v_readlane_b32 s91, v255, 27
	v_readlane_b32 s92, v255, 28
	v_readlane_b32 s93, v255, 29
	v_readlane_b32 s94, v255, 30
	v_readlane_b32 s95, v255, 31
	v_readlane_b32 s96, v255, 32
	v_readlane_b32 s97, v255, 33
	v_readlane_b32 s98, v255, 34
	v_readlane_b32 s99, v255, 35
	v_readlane_b32 vcc_lo, v255, 36
	v_readlane_b32 vcc_hi, v255, 37
	s_nop 4
